# GEMM k-step second half: next group's fragment reads issued inside the current MFMA group (behind the last MFMA reading the overwritten registers)
# speedup vs baseline: 1.0225x; 1.0005x over previous
.LBB0_888:
	s_waitcnt vmcnt(8)
	ds_read_b128 v[134:137], v151 offset:32768
	ds_read_b128 v[160:163], v152 offset:49152
	ds_read_b128 v[164:167], v151 offset:36864
	ds_read_b128 v[168:171], v152 offset:53248
	ds_write_b128 v141, v[64:67]
	ds_write_b128 v141, v[72:75] offset:16384
	s_andn2_b64 vcc, exec, s[8:9]
	s_waitcnt lgkmcnt(2)
	v_mfma_f32_32x32x16_bf16 v[48:63], v[134:137], v[160:163], v[48:63]
	v_mfma_f32_32x32x16_bf16 v[32:47], v[134:137], v[168:171], v[32:47]
	ds_read_b128 v[134:137], v153 offset:32768
	v_mfma_f32_32x32x16_bf16 v[16:31], v[164:167], v[160:163], v[16:31]
	ds_read_b128 v[160:163], v154 offset:49152
	v_mfma_f32_32x32x16_bf16 v[0:15], v[164:167], v[168:171], v[0:15]
	ds_read_b128 v[164:167], v153 offset:36864
	ds_read_b128 v[168:171], v154 offset:53248
	ds_write_b128 v141, v[80:83] offset:4096
	ds_write_b128 v141, v[88:91] offset:20480
	s_waitcnt lgkmcnt(2)
	v_mfma_f32_32x32x16_bf16 v[48:63], v[134:137], v[160:163], v[48:63]
	v_mfma_f32_32x32x16_bf16 v[32:47], v[134:137], v[168:171], v[32:47]
	ds_read_b128 v[134:137], v155 offset:32768
	v_mfma_f32_32x32x16_bf16 v[16:31], v[164:167], v[160:163], v[16:31]
	ds_read_b128 v[160:163], v156 offset:49152
	ds_read_b128 v[152:155], v155 offset:36864
	v_mfma_f32_32x32x16_bf16 v[0:15], v[164:167], v[168:171], v[0:15]
	ds_read_b128 v[164:167], v156 offset:53248
	ds_write_b128 v141, v[96:99] offset:8192
	ds_write_b128 v141, v[104:107] offset:24576
	s_waitcnt lgkmcnt(2)
	v_mfma_f32_32x32x16_bf16 v[48:63], v[134:137], v[160:163], v[48:63]
	v_mfma_f32_32x32x16_bf16 v[32:47], v[134:137], v[164:167], v[32:47]
	ds_read_b128 v[134:137], v157 offset:32768
	v_mfma_f32_32x32x16_bf16 v[16:31], v[152:155], v[160:163], v[16:31]
	v_mfma_f32_32x32x16_bf16 v[0:15], v[152:155], v[164:167], v[0:15]
	ds_read_b128 v[152:155], v158 offset:49152
	ds_read_b128 v[160:163], v157 offset:36864
	ds_read_b128 v[156:159], v158 offset:53248
	ds_write_b128 v141, v[112:115] offset:12288
	ds_write_b128 v141, v[120:123] offset:28672
	s_waitcnt lgkmcnt(2)
	v_mfma_f32_32x32x16_bf16 v[48:63], v[134:137], v[152:155], v[48:63]
	v_mfma_f32_32x32x16_bf16 v[32:47], v[134:137], v[156:159], v[32:47]
	v_mfma_f32_32x32x16_bf16 v[16:31], v[160:163], v[152:155], v[16:31]
	v_mfma_f32_32x32x16_bf16 v[0:15], v[160:163], v[156:159], v[0:15]
	s_branch .LBB0_883

.LBB0_1012:
	s_waitcnt vmcnt(8)
	ds_read_b128 v[192:195], v153 offset:32768
	ds_read_b128 v[218:221], v155 offset:49152
	ds_read_b128 v[222:225], v153 offset:36864
	ds_read_b128 v[226:229], v155 offset:53248
	ds_write_b128 v135, v[64:67]
	ds_write_b128 v135, v[72:75] offset:16384
	s_andn2_b64 vcc, exec, s[8:9]
	s_waitcnt lgkmcnt(2)
	v_mfma_f32_32x32x16_bf16 v[32:47], v[192:195], v[218:221], v[32:47]
	v_mfma_f32_32x32x16_bf16 v[48:63], v[192:195], v[226:229], v[48:63]
	ds_read_b128 v[192:195], v157 offset:32768
	v_mfma_f32_32x32x16_bf16 v[0:15], v[222:225], v[218:221], v[0:15]
	ds_read_b128 v[218:221], v159 offset:49152
	v_mfma_f32_32x32x16_bf16 v[16:31], v[222:225], v[226:229], v[16:31]
	ds_read_b128 v[222:225], v157 offset:36864
	ds_read_b128 v[226:229], v159 offset:53248
	ds_write_b128 v135, v[80:83] offset:4096
	ds_write_b128 v135, v[88:91] offset:20480
	s_waitcnt lgkmcnt(2)
	v_mfma_f32_32x32x16_bf16 v[32:47], v[192:195], v[218:221], v[32:47]
	v_mfma_f32_32x32x16_bf16 v[48:63], v[192:195], v[226:229], v[48:63]
	ds_read_b128 v[192:195], v161 offset:32768
	v_mfma_f32_32x32x16_bf16 v[0:15], v[222:225], v[218:221], v[0:15]
	ds_read_b128 v[218:221], v163 offset:49152
	v_mfma_f32_32x32x16_bf16 v[16:31], v[222:225], v[226:229], v[16:31]
	ds_read_b128 v[222:225], v161 offset:36864
	ds_read_b128 v[226:229], v163 offset:53248
	ds_write_b128 v135, v[96:99] offset:8192
	ds_write_b128 v135, v[104:107] offset:24576
	s_waitcnt lgkmcnt(2)
	v_mfma_f32_32x32x16_bf16 v[32:47], v[192:195], v[218:221], v[32:47]
	v_mfma_f32_32x32x16_bf16 v[48:63], v[192:195], v[226:229], v[48:63]
	ds_read_b128 v[192:195], v165 offset:32768
	v_mfma_f32_32x32x16_bf16 v[0:15], v[222:225], v[218:221], v[0:15]
	ds_read_b128 v[218:221], v167 offset:49152
	v_mfma_f32_32x32x16_bf16 v[16:31], v[222:225], v[226:229], v[16:31]
	ds_read_b128 v[222:225], v165 offset:36864
	ds_read_b128 v[226:229], v167 offset:53248
	ds_write_b128 v135, v[112:115] offset:12288
	ds_write_b128 v135, v[120:123] offset:28672
	s_waitcnt lgkmcnt(2)
	v_mfma_f32_32x32x16_bf16 v[32:47], v[192:195], v[218:221], v[32:47]
	v_mfma_f32_32x32x16_bf16 v[48:63], v[192:195], v[226:229], v[48:63]
	v_mfma_f32_32x32x16_bf16 v[0:15], v[222:225], v[218:221], v[0:15]
	v_mfma_f32_32x32x16_bf16 v[16:31], v[222:225], v[226:229], v[16:31]
	s_branch .LBB0_1007

.LBB0_1510:
	s_waitcnt vmcnt(8)
	ds_read_b128 v[134:137], v145 offset:32768
	ds_read_b128 v[154:157], v146 offset:49152
	ds_read_b128 v[158:161], v145 offset:36864
	ds_read_b128 v[162:165], v146 offset:53248
	ds_write_b128 v138, v[64:67]
	ds_write_b128 v138, v[72:75] offset:16384
	s_andn2_b64 vcc, exec, s[6:7]
	s_waitcnt lgkmcnt(2)
	v_mfma_f32_32x32x16_bf16 v[48:63], v[134:137], v[154:157], v[48:63]
	v_mfma_f32_32x32x16_bf16 v[32:47], v[134:137], v[162:165], v[32:47]
	ds_read_b128 v[134:137], v147 offset:32768
	v_mfma_f32_32x32x16_bf16 v[16:31], v[158:161], v[154:157], v[16:31]
	ds_read_b128 v[154:157], v148 offset:49152
	v_mfma_f32_32x32x16_bf16 v[0:15], v[158:161], v[162:165], v[0:15]
	ds_read_b128 v[158:161], v147 offset:36864
	ds_read_b128 v[162:165], v148 offset:53248
	ds_write_b128 v138, v[80:83] offset:4096
	ds_write_b128 v138, v[88:91] offset:20480
	s_waitcnt lgkmcnt(2)
	v_mfma_f32_32x32x16_bf16 v[48:63], v[134:137], v[154:157], v[48:63]
	v_mfma_f32_32x32x16_bf16 v[32:47], v[134:137], v[162:165], v[32:47]
	ds_read_b128 v[134:137], v149 offset:32768
	v_mfma_f32_32x32x16_bf16 v[16:31], v[158:161], v[154:157], v[16:31]
	ds_read_b128 v[154:157], v150 offset:49152
	ds_read_b128 v[146:149], v149 offset:36864
	v_mfma_f32_32x32x16_bf16 v[0:15], v[158:161], v[162:165], v[0:15]
	ds_read_b128 v[158:161], v150 offset:53248
	ds_write_b128 v138, v[96:99] offset:8192
	ds_write_b128 v138, v[104:107] offset:24576
	s_waitcnt lgkmcnt(2)
	v_mfma_f32_32x32x16_bf16 v[48:63], v[134:137], v[154:157], v[48:63]
	v_mfma_f32_32x32x16_bf16 v[32:47], v[134:137], v[158:161], v[32:47]
	ds_read_b128 v[134:137], v151 offset:32768
	v_mfma_f32_32x32x16_bf16 v[16:31], v[146:149], v[154:157], v[16:31]
	v_mfma_f32_32x32x16_bf16 v[0:15], v[146:149], v[158:161], v[0:15]
	ds_read_b128 v[146:149], v152 offset:49152
	ds_read_b128 v[154:157], v151 offset:36864
	ds_read_b128 v[150:153], v152 offset:53248
	ds_write_b128 v138, v[112:115] offset:12288
	ds_write_b128 v138, v[120:123] offset:28672
	s_waitcnt lgkmcnt(2)
	v_mfma_f32_32x32x16_bf16 v[48:63], v[134:137], v[146:149], v[48:63]
	v_mfma_f32_32x32x16_bf16 v[32:47], v[134:137], v[150:153], v[32:47]
	v_mfma_f32_32x32x16_bf16 v[16:31], v[154:157], v[146:149], v[16:31]
	v_mfma_f32_32x32x16_bf16 v[0:15], v[154:157], v[150:153], v[0:15]
	s_branch .LBB0_1505
